# K-loops: 4th-segment LDS-DMA addresses via offset:128 on the 2nd-segment address registers (M0 compensated), six 64-bit VALU adds per iteration removed; no other change vs v28
# speedup vs baseline: 1.0067x; 1.0067x over previous
; #define PG8_STAGE(bufoff, gbase, voff) do { _Pragma("unroll") for (int _i = 0; _i < 2; ++_i) \
;         __builtin_amdgcn_global_load_lds((const unsigned*)((const char*)(gbase) + (voff)[_i]), (LAS unsigned*)(lds + (bufoff) + ldsw + _i * 8192), 16, 0, 0); } while (0)
; #define PG8_LDA(dst, b, h) do { _Pragma("unroll") for (int m = 0; m < 4; ++m) _Pragma("unroll") for (int k = 0; k < 2; ++k) dst[m][k] = *(const LAS bf16x8*)(lds + PG8_SA(b, h) + aoff + m * 2048 + k * 1024); } while (0)
; #define PG8_LDB(dst, b, h) do { _Pragma("unroll") for (int n = 0; n < 2; ++n) _Pragma("unroll") for (int k = 0; k < 2; ++k) dst[n][k] = *(const LAS bf16x8*)(lds + PG8_SB(b, h) + boff + n * 2048 + k * 1024); } while (0)
; #define PG8_MMA(ai, bj, At, Bt) do { __builtin_amdgcn_s_setprio(1); _Pragma("unroll") for (int m = 0; m < 4; ++m) _Pragma("unroll") for (int n = 0; n < 2; ++n) _Pragma("unroll") for (int k = 0; k < 2; ++k) \
;         acc[ai][bj][m][n] = __builtin_amdgcn_mfma_f32_16x16x32_bf16(Bt[n][k], At[m][k], acc[ai][bj][m][n], 0, 0, 0); __builtin_amdgcn_s_setprio(0); } while (0)
; #define PG8_WAIT_V(n) asm volatile("s_waitcnt vmcnt(" #n ")" ::: "memory")
; #define PG8_WAIT_L(n) asm volatile("s_waitcnt lgkmcnt(" #n ")" ::: "memory")
; #define PG8_BAR __builtin_amdgcn_s_barrier()
; #define PG8_SCHED __builtin_amdgcn_sched_barrier(0)
;     ...
;         for (int t = 0; t < nt; t += 2) {
;             const bool last = (t == nt - 2);
;             const char* a1 = cA + (size_t)(t + 1) * kstep;
;             const char* a2 = last ? nA : cA + (size_t)(t + 2) * kstep; const char* b2 = last ? nB : cB + (size_t)(t + 2) * kstep;
;             const char* a3 = a2 + kstep; const char* b3 = b2 + kstep;
;             PG8_LDB(B0, 0, 0); PG8_LDB(B1, 0, 1); PG8_SCHED; PG8_LDA(At, 0, 0); PG8_STAGE(PG8_SA(1, 1), a1 + hstepA, voffA);
;             PG8_WAIT_V(8); PG8_WAIT_L(0); PG8_BAR; PG8_MMA(0, 0, At, B0); PG8_MMA(0, 1, At, B1); PG8_BAR; PG8_SCHED;
;             PG8_LDA(At, 0, 1); PG8_STAGE(PG8_SB(0, 0), b2, voffB); PG8_STAGE(PG8_SB(0, 1), b2 + hstepB, voffB); PG8_STAGE(PG8_SA(0, 0), a2, voffA);
;             PG8_WAIT_V(8); PG8_WAIT_L(0); PG8_BAR; PG8_MMA(1, 0, At, B0); PG8_MMA(1, 1, At, B1); PG8_BAR; PG8_SCHED;
.LBB0_159:
	s_add_i32 s38, s8, 2
	s_add_u32 s26, s12, s0
	s_addc_u32 s9, s13, s1
	s_add_i32 s27, 0, 0x10000
	s_cmp_eq_u32 s63, s8
	s_cselect_b32 s9, s18, s9
	s_cselect_b32 s8, s19, s26
	s_cselect_b64 vcc, -1, 0
	s_add_i32 s26, 0, 0x14000
	v_lshl_add_u64 v[150:151], v[188:189], 0, s[0:1]
	v_add_u32_e32 v146, s27, v226
	v_add_u32_e32 v162, s26, v226
	ds_read_b128 v[134:137], v146
	ds_read_b128 v[138:141], v146 offset:1024
	ds_read_b128 v[142:145], v146 offset:2048
	ds_read_b128 v[146:149], v146 offset:3072
	v_cndmask_b32_e32 v205, v151, v132, vcc
	v_cndmask_b32_e32 v204, v150, v133, vcc
	ds_read_b128 v[150:153], v162
	ds_read_b128 v[154:157], v162 offset:1024
	ds_read_b128 v[158:161], v162 offset:2048
	ds_read_b128 v[162:165], v162 offset:3072
	v_lshl_add_u64 v[212:213], s[12:13], 0, v[130:131]
	s_add_i32 m0, s20, 0xc000
	ds_read_b128 v[166:169], v227
	ds_read_b128 v[170:173], v227 offset:1024
	ds_read_b128 v[174:177], v227 offset:2048
	ds_read_b128 v[178:181], v227 offset:3072
	ds_read_b128 v[230:233], v227 offset:4096
	ds_read_b128 v[234:237], v227 offset:5120
	ds_read_b128 v[238:241], v227 offset:6144
	ds_read_b128 v[242:245], v227 offset:7168
	global_load_lds_dwordx4 v[212:213], off
	v_lshl_add_u64 v[212:213], s[12:13], 0, v[128:129]
	s_add_i32 m0, s20, 0xe000
	s_nop 0
	global_load_lds_dwordx4 v[212:213], off
	s_waitcnt vmcnt(8)
	s_waitcnt lgkmcnt(0)
	s_barrier
	s_setprio 1
	s_waitcnt lgkmcnt(0)
	v_mfma_f32_16x16x32_bf16 v[124:127], v[134:137], v[166:169], v[124:127]
	v_mfma_f32_16x16x32_bf16 v[0:3], v[142:145], v[166:169], v[0:3]
	v_mfma_f32_16x16x32_bf16 v[120:123], v[134:137], v[174:177], v[120:123]
	v_mfma_f32_16x16x32_bf16 v[116:119], v[142:145], v[174:177], v[116:119]
	v_mfma_f32_16x16x32_bf16 v[112:115], v[134:137], v[230:233], v[112:115]
	v_mfma_f32_16x16x32_bf16 v[108:111], v[142:145], v[230:233], v[108:111]
	v_mfma_f32_16x16x32_bf16 v[104:107], v[134:137], v[238:241], v[104:107]
	v_mfma_f32_16x16x32_bf16 v[4:7], v[142:145], v[238:241], v[4:7]
	v_mfma_f32_16x16x32_bf16 v[124:127], v[138:141], v[170:173], v[124:127]
	v_mfma_f32_16x16x32_bf16 v[0:3], v[146:149], v[170:173], v[0:3]
	v_mfma_f32_16x16x32_bf16 v[120:123], v[138:141], v[178:181], v[120:123]
	v_mfma_f32_16x16x32_bf16 v[116:119], v[146:149], v[178:181], v[116:119]
	v_mfma_f32_16x16x32_bf16 v[112:115], v[138:141], v[234:237], v[112:115]
	v_mfma_f32_16x16x32_bf16 v[108:111], v[146:149], v[234:237], v[108:111]
	v_mfma_f32_16x16x32_bf16 v[104:107], v[138:141], v[242:245], v[104:107]
	v_mfma_f32_16x16x32_bf16 v[4:7], v[146:149], v[242:245], v[4:7]
	s_setprio 0
	s_setprio 1
	v_mfma_f32_16x16x32_bf16 v[100:103], v[150:153], v[166:169], v[100:103]
	v_mfma_f32_16x16x32_bf16 v[96:99], v[158:161], v[166:169], v[96:99]
	v_mfma_f32_16x16x32_bf16 v[92:95], v[150:153], v[174:177], v[92:95]
	v_mfma_f32_16x16x32_bf16 v[88:91], v[158:161], v[174:177], v[88:91]
	v_mfma_f32_16x16x32_bf16 v[84:87], v[150:153], v[230:233], v[84:87]
	v_mfma_f32_16x16x32_bf16 v[80:83], v[158:161], v[230:233], v[80:83]
	v_mfma_f32_16x16x32_bf16 v[76:79], v[150:153], v[238:241], v[76:79]
	v_mfma_f32_16x16x32_bf16 v[72:75], v[158:161], v[238:241], v[72:75]
	v_mfma_f32_16x16x32_bf16 v[100:103], v[154:157], v[170:173], v[100:103]
	v_mfma_f32_16x16x32_bf16 v[96:99], v[162:165], v[170:173], v[96:99]
	v_mfma_f32_16x16x32_bf16 v[92:95], v[154:157], v[178:181], v[92:95]
	v_mfma_f32_16x16x32_bf16 v[88:91], v[162:165], v[178:181], v[88:91]
	v_mfma_f32_16x16x32_bf16 v[84:87], v[154:157], v[234:237], v[84:87]
	v_mfma_f32_16x16x32_bf16 v[80:83], v[162:165], v[234:237], v[80:83]
	v_mfma_f32_16x16x32_bf16 v[76:79], v[154:157], v[242:245], v[76:79]
	v_mfma_f32_16x16x32_bf16 v[72:75], v[162:165], v[242:245], v[72:75]
	s_setprio 0
	s_barrier
	s_add_i32 s27, s27, s11
	v_lshl_add_u64 v[212:213], v[204:205], 0, v[192:193]
	s_mov_b32 m0, s27
	ds_read_b128 v[166:169], v227 offset:16384
	ds_read_b128 v[170:173], v227 offset:17408
	ds_read_b128 v[174:177], v227 offset:18432
	ds_read_b128 v[178:181], v227 offset:19456
	ds_read_b128 v[230:233], v227 offset:20480
	ds_read_b128 v[234:237], v227 offset:21504
	ds_read_b128 v[238:241], v227 offset:22528
	ds_read_b128 v[242:245], v227 offset:23552
	global_load_lds_dwordx4 v[212:213], off
	v_lshl_add_u64 v[218:219], v[204:205], 0, v[196:197]
	s_add_i32 m0, s27, 0x2000
	v_lshl_add_u64 v[204:205], v[204:205], 0, v[198:199]
	s_add_i32 s26, s26, s11
	global_load_lds_dwordx4 v[218:219], off
	v_lshl_add_u64 v[246:247], v[204:205], 0, v[192:193]
	s_mov_b32 m0, s26
	v_lshl_add_u64 v[204:205], v[204:205], 0, v[196:197]
	global_load_lds_dwordx4 v[246:247], off
	s_add_i32 m0, s26, 0x2000
	v_lshl_add_u64 v[248:249], s[8:9], 0, v[190:191]
	global_load_lds_dwordx4 v[204:205], off
	s_mov_b32 m0, s20
	v_lshl_add_u64 v[250:251], s[8:9], 0, v[194:195]
	global_load_lds_dwordx4 v[248:249], off
	s_mov_b32 m0, s48
	s_nop 0
	global_load_lds_dwordx4 v[250:251], off
	s_waitcnt vmcnt(8)
	s_waitcnt lgkmcnt(0)
	s_barrier
; #define PG8_STAGE(bufoff, gbase, voff) do { _Pragma("unroll") for (int _i = 0; _i < 2; ++_i) \
;         __builtin_amdgcn_global_load_lds((const unsigned*)((const char*)(gbase) + (voff)[_i]), (LAS unsigned*)(lds + (bufoff) + ldsw + _i * 8192), 16, 0, 0); } while (0)
; #define PG8_LDA(dst, b, h) do { _Pragma("unroll") for (int m = 0; m < 4; ++m) _Pragma("unroll") for (int k = 0; k < 2; ++k) dst[m][k] = *(const LAS bf16x8*)(lds + PG8_SA(b, h) + aoff + m * 2048 + k * 1024); } while (0)
; #define PG8_LDB(dst, b, h) do { _Pragma("unroll") for (int n = 0; n < 2; ++n) _Pragma("unroll") for (int k = 0; k < 2; ++k) dst[n][k] = *(const LAS bf16x8*)(lds + PG8_SB(b, h) + boff + n * 2048 + k * 1024); } while (0)
; #define PG8_MMA(ai, bj, At, Bt) do { __builtin_amdgcn_s_setprio(1); _Pragma("unroll") for (int m = 0; m < 4; ++m) _Pragma("unroll") for (int n = 0; n < 2; ++n) _Pragma("unroll") for (int k = 0; k < 2; ++k) \
;         acc[ai][bj][m][n] = __builtin_amdgcn_mfma_f32_16x16x32_bf16(Bt[n][k], At[m][k], acc[ai][bj][m][n], 0, 0, 0); __builtin_amdgcn_s_setprio(0); } while (0)
; #define PG8_WAIT_V(n) asm volatile("s_waitcnt vmcnt(" #n ")" ::: "memory")
; #define PG8_WAIT_L(n) asm volatile("s_waitcnt lgkmcnt(" #n ")" ::: "memory")
; #define PG8_BAR __builtin_amdgcn_s_barrier()
; #define PG8_SCHED __builtin_amdgcn_sched_barrier(0)
;     ...
;             PG8_WAIT_V(8); PG8_WAIT_L(0); PG8_BAR; PG8_MMA(1, 0, At, B0); PG8_MMA(1, 1, At, B1); PG8_BAR; PG8_SCHED;
;             PG8_LDB(B0, 1, 0); PG8_LDB(B1, 1, 1); PG8_SCHED; PG8_LDA(At, 1, 0); PG8_STAGE(PG8_SA(0, 1), a2 + hstepA, voffA);
;             PG8_WAIT_V(8); PG8_WAIT_L(0); PG8_BAR; PG8_MMA(0, 0, At, B0); PG8_MMA(0, 1, At, B1); PG8_BAR; PG8_SCHED;
	s_setprio 1
	s_waitcnt lgkmcnt(0)
	v_mfma_f32_16x16x32_bf16 v[68:71], v[134:137], v[166:169], v[68:71]
	v_mfma_f32_16x16x32_bf16 v[8:11], v[142:145], v[166:169], v[8:11]
	v_mfma_f32_16x16x32_bf16 v[64:67], v[134:137], v[174:177], v[64:67]
	v_mfma_f32_16x16x32_bf16 v[60:63], v[142:145], v[174:177], v[60:63]
	v_mfma_f32_16x16x32_bf16 v[56:59], v[134:137], v[230:233], v[56:59]
	v_mfma_f32_16x16x32_bf16 v[52:55], v[142:145], v[230:233], v[52:55]
	v_mfma_f32_16x16x32_bf16 v[48:51], v[134:137], v[238:241], v[48:51]
	v_mfma_f32_16x16x32_bf16 v[12:15], v[142:145], v[238:241], v[12:15]
	v_mfma_f32_16x16x32_bf16 v[68:71], v[138:141], v[170:173], v[68:71]
	v_mfma_f32_16x16x32_bf16 v[8:11], v[146:149], v[170:173], v[8:11]
	v_mfma_f32_16x16x32_bf16 v[64:67], v[138:141], v[178:181], v[64:67]
	v_mfma_f32_16x16x32_bf16 v[60:63], v[146:149], v[178:181], v[60:63]
	v_mfma_f32_16x16x32_bf16 v[56:59], v[138:141], v[234:237], v[56:59]
	v_mfma_f32_16x16x32_bf16 v[52:55], v[146:149], v[234:237], v[52:55]
	v_mfma_f32_16x16x32_bf16 v[48:51], v[138:141], v[242:245], v[48:51]
	v_mfma_f32_16x16x32_bf16 v[12:15], v[146:149], v[242:245], v[12:15]
	s_setprio 0
	s_setprio 1
	v_mfma_f32_16x16x32_bf16 v[44:47], v[150:153], v[166:169], v[44:47]
	v_mfma_f32_16x16x32_bf16 v[40:43], v[158:161], v[166:169], v[40:43]
	v_mfma_f32_16x16x32_bf16 v[36:39], v[150:153], v[174:177], v[36:39]
	v_mfma_f32_16x16x32_bf16 v[32:35], v[158:161], v[174:177], v[32:35]
	v_mfma_f32_16x16x32_bf16 v[28:31], v[150:153], v[230:233], v[28:31]
	v_mfma_f32_16x16x32_bf16 v[24:27], v[158:161], v[230:233], v[24:27]
	v_mfma_f32_16x16x32_bf16 v[20:23], v[150:153], v[238:241], v[20:23]
	v_mfma_f32_16x16x32_bf16 v[16:19], v[158:161], v[238:241], v[16:19]
	v_mfma_f32_16x16x32_bf16 v[44:47], v[154:157], v[170:173], v[44:47]
	v_mfma_f32_16x16x32_bf16 v[40:43], v[162:165], v[170:173], v[40:43]
	v_mfma_f32_16x16x32_bf16 v[36:39], v[154:157], v[178:181], v[36:39]
	v_mfma_f32_16x16x32_bf16 v[32:35], v[162:165], v[178:181], v[32:35]
	v_mfma_f32_16x16x32_bf16 v[28:31], v[154:157], v[234:237], v[28:31]
	v_mfma_f32_16x16x32_bf16 v[24:27], v[162:165], v[234:237], v[24:27]
	v_mfma_f32_16x16x32_bf16 v[20:23], v[154:157], v[242:245], v[20:23]
	v_mfma_f32_16x16x32_bf16 v[16:19], v[162:165], v[242:245], v[16:19]
	s_setprio 0
	s_barrier
	s_add_i32 s26, 0, 0x18000
	s_add_i32 s27, 0, 0x1c000
	v_add_u32_e32 v146, s26, v226
	v_add_u32_e32 v162, s27, v226
	ds_read_b128 v[134:137], v146
	ds_read_b128 v[138:141], v146 offset:1024
	ds_read_b128 v[142:145], v146 offset:2048
	ds_read_b128 v[146:149], v146 offset:3072
	ds_read_b128 v[150:153], v162
	ds_read_b128 v[154:157], v162 offset:1024
	ds_read_b128 v[158:161], v162 offset:2048
	ds_read_b128 v[162:165], v162 offset:3072
	s_add_u32 s8, s8, s10
	s_addc_u32 s9, s9, 0
	s_mov_b32 m0, s51
	v_lshl_add_u64 v[214:215], s[8:9], 0, v[190:191]
	ds_read_b128 v[166:169], v227 offset:32768
	ds_read_b128 v[170:173], v227 offset:33792
	ds_read_b128 v[174:177], v227 offset:34816
	ds_read_b128 v[178:181], v227 offset:35840
	ds_read_b128 v[230:233], v227 offset:36864
	ds_read_b128 v[234:237], v227 offset:37888
	ds_read_b128 v[238:241], v227 offset:38912
	ds_read_b128 v[242:245], v227 offset:39936
	global_load_lds_dwordx4 v[214:215], off
	v_lshl_add_u64 v[214:215], s[8:9], 0, v[194:195]
	s_mov_b32 m0, s62
	s_nop 0
	global_load_lds_dwordx4 v[214:215], off
	s_waitcnt vmcnt(8)
	s_waitcnt lgkmcnt(0)
	s_barrier
	s_setprio 1
	s_waitcnt lgkmcnt(0)
	v_mfma_f32_16x16x32_bf16 v[124:127], v[134:137], v[166:169], v[124:127]
	v_mfma_f32_16x16x32_bf16 v[0:3], v[142:145], v[166:169], v[0:3]
	v_mfma_f32_16x16x32_bf16 v[120:123], v[134:137], v[174:177], v[120:123]
	v_mfma_f32_16x16x32_bf16 v[116:119], v[142:145], v[174:177], v[116:119]
	v_mfma_f32_16x16x32_bf16 v[112:115], v[134:137], v[230:233], v[112:115]
	v_mfma_f32_16x16x32_bf16 v[108:111], v[142:145], v[230:233], v[108:111]
	v_mfma_f32_16x16x32_bf16 v[104:107], v[134:137], v[238:241], v[104:107]
	v_mfma_f32_16x16x32_bf16 v[4:7], v[142:145], v[238:241], v[4:7]
	v_mfma_f32_16x16x32_bf16 v[124:127], v[138:141], v[170:173], v[124:127]
	v_mfma_f32_16x16x32_bf16 v[0:3], v[146:149], v[170:173], v[0:3]
	v_mfma_f32_16x16x32_bf16 v[120:123], v[138:141], v[178:181], v[120:123]
	v_mfma_f32_16x16x32_bf16 v[116:119], v[146:149], v[178:181], v[116:119]
	v_mfma_f32_16x16x32_bf16 v[112:115], v[138:141], v[234:237], v[112:115]
	v_mfma_f32_16x16x32_bf16 v[108:111], v[146:149], v[234:237], v[108:111]
	v_mfma_f32_16x16x32_bf16 v[104:107], v[138:141], v[242:245], v[104:107]
	v_mfma_f32_16x16x32_bf16 v[4:7], v[146:149], v[242:245], v[4:7]
	s_setprio 0
	s_setprio 1
	v_mfma_f32_16x16x32_bf16 v[100:103], v[150:153], v[166:169], v[100:103]
	v_mfma_f32_16x16x32_bf16 v[96:99], v[158:161], v[166:169], v[96:99]
	v_mfma_f32_16x16x32_bf16 v[92:95], v[150:153], v[174:177], v[92:95]
	v_mfma_f32_16x16x32_bf16 v[88:91], v[158:161], v[174:177], v[88:91]
	v_mfma_f32_16x16x32_bf16 v[84:87], v[150:153], v[230:233], v[84:87]
	v_mfma_f32_16x16x32_bf16 v[80:83], v[158:161], v[230:233], v[80:83]
	v_mfma_f32_16x16x32_bf16 v[76:79], v[150:153], v[238:241], v[76:79]
	v_mfma_f32_16x16x32_bf16 v[72:75], v[158:161], v[238:241], v[72:75]
	v_mfma_f32_16x16x32_bf16 v[100:103], v[154:157], v[170:173], v[100:103]
	v_mfma_f32_16x16x32_bf16 v[96:99], v[162:165], v[170:173], v[96:99]
	v_mfma_f32_16x16x32_bf16 v[92:95], v[154:157], v[178:181], v[92:95]
	v_mfma_f32_16x16x32_bf16 v[88:91], v[162:165], v[178:181], v[88:91]
	v_mfma_f32_16x16x32_bf16 v[84:87], v[154:157], v[234:237], v[84:87]
	v_mfma_f32_16x16x32_bf16 v[80:83], v[162:165], v[234:237], v[80:83]
	v_mfma_f32_16x16x32_bf16 v[76:79], v[154:157], v[242:245], v[76:79]
	v_mfma_f32_16x16x32_bf16 v[72:75], v[162:165], v[242:245], v[72:75]
	s_setprio 0
	s_barrier
; #define PG8_STAGE(bufoff, gbase, voff) do { _Pragma("unroll") for (int _i = 0; _i < 2; ++_i) \
;         __builtin_amdgcn_global_load_lds((const unsigned*)((const char*)(gbase) + (voff)[_i]), (LAS unsigned*)(lds + (bufoff) + ldsw + _i * 8192), 16, 0, 0); } while (0)
; #define PG8_LDA(dst, b, h) do { _Pragma("unroll") for (int m = 0; m < 4; ++m) _Pragma("unroll") for (int k = 0; k < 2; ++k) dst[m][k] = *(const LAS bf16x8*)(lds + PG8_SA(b, h) + aoff + m * 2048 + k * 1024); } while (0)
; #define PG8_MMA(ai, bj, At, Bt) do { __builtin_amdgcn_s_setprio(1); _Pragma("unroll") for (int m = 0; m < 4; ++m) _Pragma("unroll") for (int n = 0; n < 2; ++n) _Pragma("unroll") for (int k = 0; k < 2; ++k) \
;         acc[ai][bj][m][n] = __builtin_amdgcn_mfma_f32_16x16x32_bf16(Bt[n][k], At[m][k], acc[ai][bj][m][n], 0, 0, 0); __builtin_amdgcn_s_setprio(0); } while (0)
; #define PG8_WAIT_V(n) asm volatile("s_waitcnt vmcnt(" #n ")" ::: "memory")
; #define PG8_WAIT_L(n) asm volatile("s_waitcnt lgkmcnt(" #n ")" ::: "memory")
; #define PG8_BAR __builtin_amdgcn_s_barrier()
; #define PG8_SCHED __builtin_amdgcn_sched_barrier(0)
;     ...
;             PG8_LDA(At, 1, 1); PG8_STAGE(PG8_SB(1, 0), b3, voffB); PG8_STAGE(PG8_SB(1, 1), b3 + hstepB, voffB); PG8_STAGE(PG8_SA(1, 0), a3, voffA);
;             PG8_WAIT_V(8); PG8_WAIT_L(0); PG8_BAR; PG8_MMA(1, 0, At, B0); PG8_MMA(1, 1, At, B1); PG8_BAR; PG8_SCHED;
;         }
;         if (wr == 0) PG8_BAR;
	s_add_i32 s8, s26, s11
	s_add_i32 m0, s8, 0xffffff80
	ds_read_b128 v[166:169], v227 offset:49152
	ds_read_b128 v[170:173], v227 offset:50176
	ds_read_b128 v[174:177], v227 offset:51200
	ds_read_b128 v[178:181], v227 offset:52224
	ds_read_b128 v[230:233], v227 offset:53248
	ds_read_b128 v[234:237], v227 offset:54272
	ds_read_b128 v[238:241], v227 offset:55296
	ds_read_b128 v[242:245], v227 offset:56320
	global_load_lds_dwordx4 v[212:213], off offset:128
	s_add_i32 m0, s8, 0x1f80
	s_add_i32 s8, s27, s11
	global_load_lds_dwordx4 v[218:219], off offset:128
	s_add_i32 m0, s8, 0xffffff80
	s_nop 0
	global_load_lds_dwordx4 v[246:247], off offset:128
	s_add_i32 m0, s8, 0x1f80
	s_nop 0
	global_load_lds_dwordx4 v[204:205], off offset:128
	s_add_i32 m0, s65, 0xffffff80
	s_nop 0
	global_load_lds_dwordx4 v[248:249], off offset:128
	s_add_i32 m0, s49, 0xffffff80
	s_nop 0
	global_load_lds_dwordx4 v[250:251], off offset:128
	s_waitcnt vmcnt(8)
	s_waitcnt lgkmcnt(0)
	s_barrier
	s_setprio 1
	s_waitcnt lgkmcnt(0)
	v_mfma_f32_16x16x32_bf16 v[68:71], v[134:137], v[166:169], v[68:71]
	v_mfma_f32_16x16x32_bf16 v[8:11], v[142:145], v[166:169], v[8:11]
	v_mfma_f32_16x16x32_bf16 v[64:67], v[134:137], v[174:177], v[64:67]
	v_mfma_f32_16x16x32_bf16 v[60:63], v[142:145], v[174:177], v[60:63]
	v_mfma_f32_16x16x32_bf16 v[56:59], v[134:137], v[230:233], v[56:59]
	v_mfma_f32_16x16x32_bf16 v[52:55], v[142:145], v[230:233], v[52:55]
	v_mfma_f32_16x16x32_bf16 v[48:51], v[134:137], v[238:241], v[48:51]
	v_mfma_f32_16x16x32_bf16 v[12:15], v[142:145], v[238:241], v[12:15]
	v_mfma_f32_16x16x32_bf16 v[68:71], v[138:141], v[170:173], v[68:71]
	v_mfma_f32_16x16x32_bf16 v[8:11], v[146:149], v[170:173], v[8:11]
	v_mfma_f32_16x16x32_bf16 v[64:67], v[138:141], v[178:181], v[64:67]
	v_mfma_f32_16x16x32_bf16 v[60:63], v[146:149], v[178:181], v[60:63]
	v_mfma_f32_16x16x32_bf16 v[56:59], v[138:141], v[234:237], v[56:59]
	v_mfma_f32_16x16x32_bf16 v[52:55], v[146:149], v[234:237], v[52:55]
	v_mfma_f32_16x16x32_bf16 v[48:51], v[138:141], v[242:245], v[48:51]
	v_mfma_f32_16x16x32_bf16 v[12:15], v[146:149], v[242:245], v[12:15]
	s_setprio 0
	s_setprio 1
	v_mfma_f32_16x16x32_bf16 v[44:47], v[150:153], v[166:169], v[44:47]
	v_mfma_f32_16x16x32_bf16 v[40:43], v[158:161], v[166:169], v[40:43]
	v_mfma_f32_16x16x32_bf16 v[36:39], v[150:153], v[174:177], v[36:39]
	v_mfma_f32_16x16x32_bf16 v[32:35], v[158:161], v[174:177], v[32:35]
	v_mfma_f32_16x16x32_bf16 v[28:31], v[150:153], v[230:233], v[28:31]
	v_mfma_f32_16x16x32_bf16 v[24:27], v[158:161], v[230:233], v[24:27]
	v_mfma_f32_16x16x32_bf16 v[20:23], v[150:153], v[238:241], v[20:23]
	v_mfma_f32_16x16x32_bf16 v[16:19], v[158:161], v[238:241], v[16:19]
	v_mfma_f32_16x16x32_bf16 v[44:47], v[154:157], v[170:173], v[44:47]
	v_mfma_f32_16x16x32_bf16 v[40:43], v[162:165], v[170:173], v[40:43]
	v_mfma_f32_16x16x32_bf16 v[36:39], v[154:157], v[178:181], v[36:39]
	v_mfma_f32_16x16x32_bf16 v[32:35], v[162:165], v[178:181], v[32:35]
	v_mfma_f32_16x16x32_bf16 v[28:31], v[154:157], v[234:237], v[28:31]
	v_mfma_f32_16x16x32_bf16 v[24:27], v[162:165], v[234:237], v[24:27]
	v_mfma_f32_16x16x32_bf16 v[20:23], v[154:157], v[242:245], v[20:23]
	v_mfma_f32_16x16x32_bf16 v[16:19], v[162:165], v[242:245], v[16:19]
	s_setprio 0
	s_barrier
	s_add_u32 s0, s0, 0x100
	s_addc_u32 s1, s1, 0
	v_lshl_add_u64 v[130:131], v[130:131], 0, s[94:95]
	v_lshl_add_u64 v[128:129], v[128:129], 0, s[94:95]
	s_cmp_ge_u32 s38, s52
	s_mov_b32 s8, s38
	s_cbranch_scc0 .LBB0_159
	v_readlane_b32 s0, v254, 50
	v_readlane_b32 s1, v254, 51
	s_and_b64 vcc, exec, s[0:1]
	s_movk_i32 s67, 0xfe
	s_cbranch_vccz .LBB0_162
	s_barrier

; #define PG8_STAGE(bufoff, gbase, voff) do { _Pragma("unroll") for (int _i = 0; _i < 2; ++_i) \
;         __builtin_amdgcn_global_load_lds((const unsigned*)((const char*)(gbase) + (voff)[_i]), (LAS unsigned*)(lds + (bufoff) + ldsw + _i * 8192), 16, 0, 0); } while (0)
; #define PG8_LDA(dst, b, h) do { _Pragma("unroll") for (int m = 0; m < 4; ++m) _Pragma("unroll") for (int k = 0; k < 2; ++k) dst[m][k] = *(const LAS bf16x8*)(lds + PG8_SA(b, h) + aoff + m * 2048 + k * 1024); } while (0)
; #define PG8_LDB(dst, b, h) do { _Pragma("unroll") for (int n = 0; n < 2; ++n) _Pragma("unroll") for (int k = 0; k < 2; ++k) dst[n][k] = *(const LAS bf16x8*)(lds + PG8_SB(b, h) + boff + n * 2048 + k * 1024); } while (0)
; #define PG8_MMA(ai, bj, At, Bt) do { __builtin_amdgcn_s_setprio(1); _Pragma("unroll") for (int m = 0; m < 4; ++m) _Pragma("unroll") for (int n = 0; n < 2; ++n) _Pragma("unroll") for (int k = 0; k < 2; ++k) \
;         acc[ai][bj][m][n] = __builtin_amdgcn_mfma_f32_16x16x32_bf16(Bt[n][k], At[m][k], acc[ai][bj][m][n], 0, 0, 0); __builtin_amdgcn_s_setprio(0); } while (0)
; #define PG8_WAIT_V(n) asm volatile("s_waitcnt vmcnt(" #n ")" ::: "memory")
; #define PG8_WAIT_L(n) asm volatile("s_waitcnt lgkmcnt(" #n ")" ::: "memory")
; #define PG8_BAR __builtin_amdgcn_s_barrier()
; #define PG8_SCHED __builtin_amdgcn_sched_barrier(0)
;     ...
;         for (int t = 0; t < nt; t += 2) {
;             const bool last = (t == nt - 2);
;             const char* a1 = cA + (size_t)(t + 1) * kstep;
;             const char* a2 = last ? nA : cA + (size_t)(t + 2) * kstep; const char* b2 = last ? nB : cB + (size_t)(t + 2) * kstep;
;             const char* a3 = a2 + kstep; const char* b3 = b2 + kstep;
;             PG8_LDB(B0, 0, 0); PG8_LDB(B1, 0, 1); PG8_SCHED; PG8_LDA(At, 0, 0); PG8_STAGE(PG8_SA(1, 1), a1 + hstepA, voffA);
;             PG8_WAIT_V(8); PG8_WAIT_L(0); PG8_BAR; PG8_MMA(0, 0, At, B0); PG8_MMA(0, 1, At, B1); PG8_BAR; PG8_SCHED;
;             PG8_LDA(At, 0, 1); PG8_STAGE(PG8_SB(0, 0), b2, voffB); PG8_STAGE(PG8_SB(0, 1), b2 + hstepB, voffB); PG8_STAGE(PG8_SA(0, 0), a2, voffA);
;             PG8_WAIT_V(8); PG8_WAIT_L(0); PG8_BAR; PG8_MMA(1, 0, At, B0); PG8_MMA(1, 1, At, B1); PG8_BAR; PG8_SCHED;
.LBB0_318:
	s_add_i32 s57, s38, 2
	s_add_u32 s19, s2, s0
	s_addc_u32 s27, s3, s1
	s_add_i32 s58, 0, 0x10000
	s_cmp_eq_u32 s51, s38
	s_cselect_b32 s39, s13, s27
	s_cselect_b32 s38, s56, s19
	s_cselect_b64 vcc, -1, 0
	s_add_i32 s19, 0, 0x14000
	v_lshl_add_u64 v[150:151], v[160:161], 0, s[0:1]
	v_add_u32_e32 v146, s58, v181
	s_waitcnt lgkmcnt(0)
	v_add_u32_e32 v178, s19, v181
	ds_read_b128 v[134:137], v146
	ds_read_b128 v[138:141], v146 offset:1024
	ds_read_b128 v[142:145], v146 offset:2048
	ds_read_b128 v[146:149], v146 offset:3072
	v_cndmask_b32_e32 v159, v151, v132, vcc
	v_cndmask_b32_e32 v158, v150, v133, vcc
	ds_read_b128 v[150:153], v178
	ds_read_b128 v[154:157], v178 offset:1024
	ds_read_b128 v[174:177], v178 offset:2048
	ds_read_b128 v[190:193], v178 offset:3072
	v_lshl_add_u64 v[178:179], s[2:3], 0, v[130:131]
	s_add_i32 m0, s11, 0xc000
	ds_read_b128 v[194:197], v188
	ds_read_b128 v[198:201], v188 offset:1024
	ds_read_b128 v[202:205], v188 offset:2048
	ds_read_b128 v[224:227], v188 offset:3072
	ds_read_b128 v[228:231], v188 offset:4096
	ds_read_b128 v[232:235], v188 offset:5120
	ds_read_b128 v[236:239], v188 offset:6144
	ds_read_b128 v[240:243], v188 offset:7168
	global_load_lds_dwordx4 v[178:179], off
	v_lshl_add_u64 v[178:179], s[2:3], 0, v[128:129]
	s_add_i32 m0, s11, 0xe000
	s_nop 0
	global_load_lds_dwordx4 v[178:179], off
	s_waitcnt vmcnt(8)
	s_waitcnt lgkmcnt(0)
	s_barrier
	s_setprio 1
	s_waitcnt lgkmcnt(0)
	v_mfma_f32_16x16x32_bf16 v[124:127], v[134:137], v[194:197], v[124:127]
	v_mfma_f32_16x16x32_bf16 v[120:123], v[142:145], v[194:197], v[120:123]
	v_mfma_f32_16x16x32_bf16 v[116:119], v[134:137], v[202:205], v[116:119]
	v_mfma_f32_16x16x32_bf16 v[112:115], v[142:145], v[202:205], v[112:115]
	v_mfma_f32_16x16x32_bf16 v[108:111], v[134:137], v[228:231], v[108:111]
	v_mfma_f32_16x16x32_bf16 v[104:107], v[142:145], v[228:231], v[104:107]
	v_mfma_f32_16x16x32_bf16 v[100:103], v[134:137], v[236:239], v[100:103]
	v_mfma_f32_16x16x32_bf16 v[96:99], v[142:145], v[236:239], v[96:99]
	v_mfma_f32_16x16x32_bf16 v[124:127], v[138:141], v[198:201], v[124:127]
	v_mfma_f32_16x16x32_bf16 v[120:123], v[146:149], v[198:201], v[120:123]
	v_mfma_f32_16x16x32_bf16 v[116:119], v[138:141], v[224:227], v[116:119]
	v_mfma_f32_16x16x32_bf16 v[112:115], v[146:149], v[224:227], v[112:115]
	v_mfma_f32_16x16x32_bf16 v[108:111], v[138:141], v[232:235], v[108:111]
	v_mfma_f32_16x16x32_bf16 v[104:107], v[146:149], v[232:235], v[104:107]
	v_mfma_f32_16x16x32_bf16 v[100:103], v[138:141], v[240:243], v[100:103]
	v_mfma_f32_16x16x32_bf16 v[96:99], v[146:149], v[240:243], v[96:99]
	s_setprio 0
	s_setprio 1
	v_mfma_f32_16x16x32_bf16 v[92:95], v[150:153], v[194:197], v[92:95]
	v_mfma_f32_16x16x32_bf16 v[88:91], v[174:177], v[194:197], v[88:91]
	v_mfma_f32_16x16x32_bf16 v[84:87], v[150:153], v[202:205], v[84:87]
	v_mfma_f32_16x16x32_bf16 v[80:83], v[174:177], v[202:205], v[80:83]
	v_mfma_f32_16x16x32_bf16 v[76:79], v[150:153], v[228:231], v[76:79]
	v_mfma_f32_16x16x32_bf16 v[72:75], v[174:177], v[228:231], v[72:75]
	v_mfma_f32_16x16x32_bf16 v[68:71], v[150:153], v[236:239], v[68:71]
	v_mfma_f32_16x16x32_bf16 v[64:67], v[174:177], v[236:239], v[64:67]
	v_mfma_f32_16x16x32_bf16 v[92:95], v[154:157], v[198:201], v[92:95]
	v_mfma_f32_16x16x32_bf16 v[88:91], v[190:193], v[198:201], v[88:91]
	v_mfma_f32_16x16x32_bf16 v[84:87], v[154:157], v[224:227], v[84:87]
	v_mfma_f32_16x16x32_bf16 v[80:83], v[190:193], v[224:227], v[80:83]
	v_mfma_f32_16x16x32_bf16 v[76:79], v[154:157], v[232:235], v[76:79]
	v_mfma_f32_16x16x32_bf16 v[72:75], v[190:193], v[232:235], v[72:75]
	v_mfma_f32_16x16x32_bf16 v[68:71], v[154:157], v[240:243], v[68:71]
	v_mfma_f32_16x16x32_bf16 v[64:67], v[190:193], v[240:243], v[64:67]
	s_setprio 0
	s_barrier
	s_add_i32 s27, s58, s10
	v_lshl_add_u64 v[178:179], v[158:159], 0, v[164:165]
	s_mov_b32 m0, s27
	ds_read_b128 v[194:197], v188 offset:16384
	ds_read_b128 v[198:201], v188 offset:17408
	ds_read_b128 v[202:205], v188 offset:18432
	ds_read_b128 v[224:227], v188 offset:19456
	ds_read_b128 v[228:231], v188 offset:20480
	ds_read_b128 v[232:235], v188 offset:21504
	ds_read_b128 v[236:239], v188 offset:22528
	ds_read_b128 v[240:243], v188 offset:23552
	global_load_lds_dwordx4 v[178:179], off
	v_lshl_add_u64 v[212:213], v[158:159], 0, v[168:169]
	s_add_i32 m0, s27, 0x2000
	v_lshl_add_u64 v[158:159], v[158:159], 0, s[96:97]
	s_add_i32 s19, s19, s10
	global_load_lds_dwordx4 v[212:213], off
	v_lshl_add_u64 v[218:219], v[158:159], 0, v[164:165]
	s_mov_b32 m0, s19
	v_lshl_add_u64 v[158:159], v[158:159], 0, v[168:169]
	global_load_lds_dwordx4 v[218:219], off
	s_add_i32 m0, s19, 0x2000
	v_lshl_add_u64 v[244:245], s[38:39], 0, v[162:163]
	global_load_lds_dwordx4 v[158:159], off
	s_mov_b32 m0, s11
	v_lshl_add_u64 v[246:247], s[38:39], 0, v[166:167]
	global_load_lds_dwordx4 v[244:245], off
	s_mov_b32 m0, s20
	s_nop 0
	global_load_lds_dwordx4 v[246:247], off
	s_waitcnt vmcnt(8)
	s_waitcnt lgkmcnt(0)
	s_barrier
; #define PG8_STAGE(bufoff, gbase, voff) do { _Pragma("unroll") for (int _i = 0; _i < 2; ++_i) \
;         __builtin_amdgcn_global_load_lds((const unsigned*)((const char*)(gbase) + (voff)[_i]), (LAS unsigned*)(lds + (bufoff) + ldsw + _i * 8192), 16, 0, 0); } while (0)
; #define PG8_LDA(dst, b, h) do { _Pragma("unroll") for (int m = 0; m < 4; ++m) _Pragma("unroll") for (int k = 0; k < 2; ++k) dst[m][k] = *(const LAS bf16x8*)(lds + PG8_SA(b, h) + aoff + m * 2048 + k * 1024); } while (0)
; #define PG8_LDB(dst, b, h) do { _Pragma("unroll") for (int n = 0; n < 2; ++n) _Pragma("unroll") for (int k = 0; k < 2; ++k) dst[n][k] = *(const LAS bf16x8*)(lds + PG8_SB(b, h) + boff + n * 2048 + k * 1024); } while (0)
; #define PG8_MMA(ai, bj, At, Bt) do { __builtin_amdgcn_s_setprio(1); _Pragma("unroll") for (int m = 0; m < 4; ++m) _Pragma("unroll") for (int n = 0; n < 2; ++n) _Pragma("unroll") for (int k = 0; k < 2; ++k) \
;         acc[ai][bj][m][n] = __builtin_amdgcn_mfma_f32_16x16x32_bf16(Bt[n][k], At[m][k], acc[ai][bj][m][n], 0, 0, 0); __builtin_amdgcn_s_setprio(0); } while (0)
; #define PG8_WAIT_V(n) asm volatile("s_waitcnt vmcnt(" #n ")" ::: "memory")
; #define PG8_WAIT_L(n) asm volatile("s_waitcnt lgkmcnt(" #n ")" ::: "memory")
; #define PG8_BAR __builtin_amdgcn_s_barrier()
; #define PG8_SCHED __builtin_amdgcn_sched_barrier(0)
;     ...
;             PG8_WAIT_V(8); PG8_WAIT_L(0); PG8_BAR; PG8_MMA(1, 0, At, B0); PG8_MMA(1, 1, At, B1); PG8_BAR; PG8_SCHED;
;             PG8_LDB(B0, 1, 0); PG8_LDB(B1, 1, 1); PG8_SCHED; PG8_LDA(At, 1, 0); PG8_STAGE(PG8_SA(0, 1), a2 + hstepA, voffA);
;             PG8_WAIT_V(8); PG8_WAIT_L(0); PG8_BAR; PG8_MMA(0, 0, At, B0); PG8_MMA(0, 1, At, B1); PG8_BAR; PG8_SCHED;
	s_setprio 1
	s_waitcnt lgkmcnt(0)
	v_mfma_f32_16x16x32_bf16 v[60:63], v[134:137], v[194:197], v[60:63]
	v_mfma_f32_16x16x32_bf16 v[56:59], v[142:145], v[194:197], v[56:59]
	v_mfma_f32_16x16x32_bf16 v[52:55], v[134:137], v[202:205], v[52:55]
	v_mfma_f32_16x16x32_bf16 v[48:51], v[142:145], v[202:205], v[48:51]
	v_mfma_f32_16x16x32_bf16 v[44:47], v[134:137], v[228:231], v[44:47]
	v_mfma_f32_16x16x32_bf16 v[40:43], v[142:145], v[228:231], v[40:43]
	v_mfma_f32_16x16x32_bf16 v[36:39], v[134:137], v[236:239], v[36:39]
	v_mfma_f32_16x16x32_bf16 v[32:35], v[142:145], v[236:239], v[32:35]
	v_mfma_f32_16x16x32_bf16 v[60:63], v[138:141], v[198:201], v[60:63]
	v_mfma_f32_16x16x32_bf16 v[56:59], v[146:149], v[198:201], v[56:59]
	v_mfma_f32_16x16x32_bf16 v[52:55], v[138:141], v[224:227], v[52:55]
	v_mfma_f32_16x16x32_bf16 v[48:51], v[146:149], v[224:227], v[48:51]
	v_mfma_f32_16x16x32_bf16 v[44:47], v[138:141], v[232:235], v[44:47]
	v_mfma_f32_16x16x32_bf16 v[40:43], v[146:149], v[232:235], v[40:43]
	v_mfma_f32_16x16x32_bf16 v[36:39], v[138:141], v[240:243], v[36:39]
	v_mfma_f32_16x16x32_bf16 v[32:35], v[146:149], v[240:243], v[32:35]
	s_setprio 0
	s_setprio 1
	v_mfma_f32_16x16x32_bf16 v[28:31], v[150:153], v[194:197], v[28:31]
	v_mfma_f32_16x16x32_bf16 v[24:27], v[174:177], v[194:197], v[24:27]
	v_mfma_f32_16x16x32_bf16 v[20:23], v[150:153], v[202:205], v[20:23]
	v_mfma_f32_16x16x32_bf16 v[16:19], v[174:177], v[202:205], v[16:19]
	v_mfma_f32_16x16x32_bf16 v[12:15], v[150:153], v[228:231], v[12:15]
	v_mfma_f32_16x16x32_bf16 v[8:11], v[174:177], v[228:231], v[8:11]
	v_mfma_f32_16x16x32_bf16 v[4:7], v[150:153], v[236:239], v[4:7]
	v_mfma_f32_16x16x32_bf16 v[0:3], v[174:177], v[236:239], v[0:3]
	v_mfma_f32_16x16x32_bf16 v[28:31], v[154:157], v[198:201], v[28:31]
	v_mfma_f32_16x16x32_bf16 v[24:27], v[190:193], v[198:201], v[24:27]
	v_mfma_f32_16x16x32_bf16 v[20:23], v[154:157], v[224:227], v[20:23]
	v_mfma_f32_16x16x32_bf16 v[16:19], v[190:193], v[224:227], v[16:19]
	v_mfma_f32_16x16x32_bf16 v[12:15], v[154:157], v[232:235], v[12:15]
	v_mfma_f32_16x16x32_bf16 v[8:11], v[190:193], v[232:235], v[8:11]
	v_mfma_f32_16x16x32_bf16 v[4:7], v[154:157], v[240:243], v[4:7]
	v_mfma_f32_16x16x32_bf16 v[0:3], v[190:193], v[240:243], v[0:3]
	s_setprio 0
	s_barrier
	s_add_i32 s19, 0, 0x18000
	s_add_i32 s27, 0, 0x1c000
	v_add_u32_e32 v146, s19, v181
	v_add_u32_e32 v182, s27, v181
	ds_read_b128 v[134:137], v146
	ds_read_b128 v[138:141], v146 offset:1024
	ds_read_b128 v[142:145], v146 offset:2048
	ds_read_b128 v[146:149], v146 offset:3072
	ds_read_b128 v[150:153], v182
	ds_read_b128 v[154:157], v182 offset:1024
	ds_read_b128 v[174:177], v182 offset:2048
	ds_read_b128 v[190:193], v182 offset:3072
	s_add_u32 s38, s38, s96
	s_addc_u32 s39, s39, 0
	s_mov_b32 m0, s48
	v_lshl_add_u64 v[248:249], s[38:39], 0, v[162:163]
	ds_read_b128 v[194:197], v188 offset:32768
	ds_read_b128 v[198:201], v188 offset:33792
	ds_read_b128 v[202:205], v188 offset:34816
	ds_read_b128 v[224:227], v188 offset:35840
	ds_read_b128 v[228:231], v188 offset:36864
	ds_read_b128 v[232:235], v188 offset:37888
	ds_read_b128 v[236:239], v188 offset:38912
	ds_read_b128 v[240:243], v188 offset:39936
	global_load_lds_dwordx4 v[248:249], off
	v_lshl_add_u64 v[248:249], s[38:39], 0, v[166:167]
	s_mov_b32 m0, s49
	s_nop 0
	global_load_lds_dwordx4 v[248:249], off
	s_waitcnt vmcnt(8)
	s_waitcnt lgkmcnt(0)
	s_barrier
	s_setprio 1
	s_waitcnt lgkmcnt(0)
	v_mfma_f32_16x16x32_bf16 v[124:127], v[134:137], v[194:197], v[124:127]
	v_mfma_f32_16x16x32_bf16 v[120:123], v[142:145], v[194:197], v[120:123]
	v_mfma_f32_16x16x32_bf16 v[116:119], v[134:137], v[202:205], v[116:119]
	v_mfma_f32_16x16x32_bf16 v[112:115], v[142:145], v[202:205], v[112:115]
	v_mfma_f32_16x16x32_bf16 v[108:111], v[134:137], v[228:231], v[108:111]
	v_mfma_f32_16x16x32_bf16 v[104:107], v[142:145], v[228:231], v[104:107]
	v_mfma_f32_16x16x32_bf16 v[100:103], v[134:137], v[236:239], v[100:103]
	v_mfma_f32_16x16x32_bf16 v[96:99], v[142:145], v[236:239], v[96:99]
	v_mfma_f32_16x16x32_bf16 v[124:127], v[138:141], v[198:201], v[124:127]
	v_mfma_f32_16x16x32_bf16 v[120:123], v[146:149], v[198:201], v[120:123]
	v_mfma_f32_16x16x32_bf16 v[116:119], v[138:141], v[224:227], v[116:119]
	v_mfma_f32_16x16x32_bf16 v[112:115], v[146:149], v[224:227], v[112:115]
	v_mfma_f32_16x16x32_bf16 v[108:111], v[138:141], v[232:235], v[108:111]
	v_mfma_f32_16x16x32_bf16 v[104:107], v[146:149], v[232:235], v[104:107]
	v_mfma_f32_16x16x32_bf16 v[100:103], v[138:141], v[240:243], v[100:103]
	v_mfma_f32_16x16x32_bf16 v[96:99], v[146:149], v[240:243], v[96:99]
	s_setprio 0
	s_setprio 1
	v_mfma_f32_16x16x32_bf16 v[92:95], v[150:153], v[194:197], v[92:95]
	v_mfma_f32_16x16x32_bf16 v[88:91], v[174:177], v[194:197], v[88:91]
	v_mfma_f32_16x16x32_bf16 v[84:87], v[150:153], v[202:205], v[84:87]
	v_mfma_f32_16x16x32_bf16 v[80:83], v[174:177], v[202:205], v[80:83]
	v_mfma_f32_16x16x32_bf16 v[76:79], v[150:153], v[228:231], v[76:79]
	v_mfma_f32_16x16x32_bf16 v[72:75], v[174:177], v[228:231], v[72:75]
	v_mfma_f32_16x16x32_bf16 v[68:71], v[150:153], v[236:239], v[68:71]
	v_mfma_f32_16x16x32_bf16 v[64:67], v[174:177], v[236:239], v[64:67]
	v_mfma_f32_16x16x32_bf16 v[92:95], v[154:157], v[198:201], v[92:95]
	v_mfma_f32_16x16x32_bf16 v[88:91], v[190:193], v[198:201], v[88:91]
	v_mfma_f32_16x16x32_bf16 v[84:87], v[154:157], v[224:227], v[84:87]
	v_mfma_f32_16x16x32_bf16 v[80:83], v[190:193], v[224:227], v[80:83]
	v_mfma_f32_16x16x32_bf16 v[76:79], v[154:157], v[232:235], v[76:79]
	v_mfma_f32_16x16x32_bf16 v[72:75], v[190:193], v[232:235], v[72:75]
	v_mfma_f32_16x16x32_bf16 v[68:71], v[154:157], v[240:243], v[68:71]
	v_mfma_f32_16x16x32_bf16 v[64:67], v[190:193], v[240:243], v[64:67]
	s_setprio 0
	s_barrier
; #define PG8_STAGE(bufoff, gbase, voff) do { _Pragma("unroll") for (int _i = 0; _i < 2; ++_i) \
;         __builtin_amdgcn_global_load_lds((const unsigned*)((const char*)(gbase) + (voff)[_i]), (LAS unsigned*)(lds + (bufoff) + ldsw + _i * 8192), 16, 0, 0); } while (0)
; #define PG8_LDA(dst, b, h) do { _Pragma("unroll") for (int m = 0; m < 4; ++m) _Pragma("unroll") for (int k = 0; k < 2; ++k) dst[m][k] = *(const LAS bf16x8*)(lds + PG8_SA(b, h) + aoff + m * 2048 + k * 1024); } while (0)
; #define PG8_MMA(ai, bj, At, Bt) do { __builtin_amdgcn_s_setprio(1); _Pragma("unroll") for (int m = 0; m < 4; ++m) _Pragma("unroll") for (int n = 0; n < 2; ++n) _Pragma("unroll") for (int k = 0; k < 2; ++k) \
;         acc[ai][bj][m][n] = __builtin_amdgcn_mfma_f32_16x16x32_bf16(Bt[n][k], At[m][k], acc[ai][bj][m][n], 0, 0, 0); __builtin_amdgcn_s_setprio(0); } while (0)
; #define PG8_WAIT_V(n) asm volatile("s_waitcnt vmcnt(" #n ")" ::: "memory")
; #define PG8_WAIT_L(n) asm volatile("s_waitcnt lgkmcnt(" #n ")" ::: "memory")
; #define PG8_BAR __builtin_amdgcn_s_barrier()
; #define PG8_SCHED __builtin_amdgcn_sched_barrier(0)
;     ...
;             PG8_LDA(At, 1, 1); PG8_STAGE(PG8_SB(1, 0), b3, voffB); PG8_STAGE(PG8_SB(1, 1), b3 + hstepB, voffB); PG8_STAGE(PG8_SA(1, 0), a3, voffA);
;             PG8_WAIT_V(8); PG8_WAIT_L(0); PG8_BAR; PG8_MMA(1, 0, At, B0); PG8_MMA(1, 1, At, B1); PG8_BAR; PG8_SCHED;
;         }
;         if (wr == 0) PG8_BAR;
	s_add_i32 s19, s19, s10
	s_add_i32 m0, s19, 0xffffff80
	ds_read_b128 v[194:197], v188 offset:49152
	ds_read_b128 v[198:201], v188 offset:50176
	ds_read_b128 v[202:205], v188 offset:51200
	ds_read_b128 v[224:227], v188 offset:52224
	ds_read_b128 v[228:231], v188 offset:53248
	ds_read_b128 v[232:235], v188 offset:54272
	ds_read_b128 v[236:239], v188 offset:55296
	ds_read_b128 v[240:243], v188 offset:56320
	global_load_lds_dwordx4 v[178:179], off offset:128
	s_add_i32 m0, s19, 0x1f80
	s_add_i32 s19, s27, s10
	global_load_lds_dwordx4 v[212:213], off offset:128
	s_add_i32 m0, s19, 0xffffff80
	s_nop 0
	global_load_lds_dwordx4 v[218:219], off offset:128
	s_add_i32 m0, s19, 0x1f80
	s_nop 0
	global_load_lds_dwordx4 v[158:159], off offset:128
	s_add_i32 m0, s62, 0xffffff80
	s_nop 0
	global_load_lds_dwordx4 v[244:245], off offset:128
	s_add_i32 m0, s63, 0xffffff80
	s_nop 0
	global_load_lds_dwordx4 v[246:247], off offset:128
	s_waitcnt vmcnt(8)
	s_waitcnt lgkmcnt(0)
	s_barrier
	s_setprio 1
	s_waitcnt lgkmcnt(0)
	v_mfma_f32_16x16x32_bf16 v[60:63], v[134:137], v[194:197], v[60:63]
	v_mfma_f32_16x16x32_bf16 v[56:59], v[142:145], v[194:197], v[56:59]
	v_mfma_f32_16x16x32_bf16 v[52:55], v[134:137], v[202:205], v[52:55]
	v_mfma_f32_16x16x32_bf16 v[48:51], v[142:145], v[202:205], v[48:51]
	v_mfma_f32_16x16x32_bf16 v[44:47], v[134:137], v[228:231], v[44:47]
	v_mfma_f32_16x16x32_bf16 v[40:43], v[142:145], v[228:231], v[40:43]
	v_mfma_f32_16x16x32_bf16 v[36:39], v[134:137], v[236:239], v[36:39]
	v_mfma_f32_16x16x32_bf16 v[32:35], v[142:145], v[236:239], v[32:35]
	v_mfma_f32_16x16x32_bf16 v[60:63], v[138:141], v[198:201], v[60:63]
	v_mfma_f32_16x16x32_bf16 v[56:59], v[146:149], v[198:201], v[56:59]
	v_mfma_f32_16x16x32_bf16 v[52:55], v[138:141], v[224:227], v[52:55]
	v_mfma_f32_16x16x32_bf16 v[48:51], v[146:149], v[224:227], v[48:51]
	v_mfma_f32_16x16x32_bf16 v[44:47], v[138:141], v[232:235], v[44:47]
	v_mfma_f32_16x16x32_bf16 v[40:43], v[146:149], v[232:235], v[40:43]
	v_mfma_f32_16x16x32_bf16 v[36:39], v[138:141], v[240:243], v[36:39]
	v_mfma_f32_16x16x32_bf16 v[32:35], v[146:149], v[240:243], v[32:35]
	s_setprio 0
	s_setprio 1
	v_mfma_f32_16x16x32_bf16 v[28:31], v[150:153], v[194:197], v[28:31]
	v_mfma_f32_16x16x32_bf16 v[24:27], v[174:177], v[194:197], v[24:27]
	v_mfma_f32_16x16x32_bf16 v[20:23], v[150:153], v[202:205], v[20:23]
	v_mfma_f32_16x16x32_bf16 v[16:19], v[174:177], v[202:205], v[16:19]
	v_mfma_f32_16x16x32_bf16 v[12:15], v[150:153], v[228:231], v[12:15]
	v_mfma_f32_16x16x32_bf16 v[8:11], v[174:177], v[228:231], v[8:11]
	v_mfma_f32_16x16x32_bf16 v[4:7], v[150:153], v[236:239], v[4:7]
	v_mfma_f32_16x16x32_bf16 v[0:3], v[174:177], v[236:239], v[0:3]
	v_mfma_f32_16x16x32_bf16 v[28:31], v[154:157], v[198:201], v[28:31]
	v_mfma_f32_16x16x32_bf16 v[24:27], v[190:193], v[198:201], v[24:27]
	v_mfma_f32_16x16x32_bf16 v[20:23], v[154:157], v[224:227], v[20:23]
	v_mfma_f32_16x16x32_bf16 v[16:19], v[190:193], v[224:227], v[16:19]
	v_mfma_f32_16x16x32_bf16 v[12:15], v[154:157], v[232:235], v[12:15]
	v_mfma_f32_16x16x32_bf16 v[8:11], v[190:193], v[232:235], v[8:11]
	v_mfma_f32_16x16x32_bf16 v[4:7], v[154:157], v[240:243], v[4:7]
	v_mfma_f32_16x16x32_bf16 v[0:3], v[190:193], v[240:243], v[0:3]
	s_setprio 0
	s_barrier
	s_add_u32 s0, s0, 0x100
	s_addc_u32 s1, s1, 0
	v_lshl_add_u64 v[130:131], v[130:131], 0, s[94:95]
	v_lshl_add_u64 v[128:129], v[128:129], 0, s[94:95]
	s_cmp_ge_u32 s57, s16
	s_mov_b32 s38, s57
	s_cbranch_scc0 .LBB0_318
	v_readlane_b32 s0, v254, 50
	v_readlane_b32 s1, v254, 51
	s_and_b64 vcc, exec, s[0:1]
	s_mov_b32 s68, 0x134000
	s_mov_b32 s69, 0x160000
	s_cbranch_vccz .LBB0_321
	s_barrier

; #define PG8_STAGE(bufoff, gbase, voff) do { _Pragma("unroll") for (int _i = 0; _i < 2; ++_i) \
;         __builtin_amdgcn_global_load_lds((const unsigned*)((const char*)(gbase) + (voff)[_i]), (LAS unsigned*)(lds + (bufoff) + ldsw + _i * 8192), 16, 0, 0); } while (0)
; #define PG8_LDA(dst, b, h) do { _Pragma("unroll") for (int m = 0; m < 4; ++m) _Pragma("unroll") for (int k = 0; k < 2; ++k) dst[m][k] = *(const LAS bf16x8*)(lds + PG8_SA(b, h) + aoff + m * 2048 + k * 1024); } while (0)
; #define PG8_LDB(dst, b, h) do { _Pragma("unroll") for (int n = 0; n < 2; ++n) _Pragma("unroll") for (int k = 0; k < 2; ++k) dst[n][k] = *(const LAS bf16x8*)(lds + PG8_SB(b, h) + boff + n * 2048 + k * 1024); } while (0)
; #define PG8_MMA(ai, bj, At, Bt) do { __builtin_amdgcn_s_setprio(1); _Pragma("unroll") for (int m = 0; m < 4; ++m) _Pragma("unroll") for (int n = 0; n < 2; ++n) _Pragma("unroll") for (int k = 0; k < 2; ++k) \
;         acc[ai][bj][m][n] = __builtin_amdgcn_mfma_f32_16x16x32_bf16(Bt[n][k], At[m][k], acc[ai][bj][m][n], 0, 0, 0); __builtin_amdgcn_s_setprio(0); } while (0)
; #define PG8_WAIT_V(n) asm volatile("s_waitcnt vmcnt(" #n ")" ::: "memory")
; #define PG8_WAIT_L(n) asm volatile("s_waitcnt lgkmcnt(" #n ")" ::: "memory")
; #define PG8_BAR __builtin_amdgcn_s_barrier()
; #define PG8_SCHED __builtin_amdgcn_sched_barrier(0)
;     ...
;         for (int t = 0; t < nt; t += 2) {
;             const bool last = (t == nt - 2);
;             const char* a1 = cA + (size_t)(t + 1) * kstep;
;             const char* a2 = last ? nA : cA + (size_t)(t + 2) * kstep; const char* b2 = last ? nB : cB + (size_t)(t + 2) * kstep;
;             const char* a3 = a2 + kstep; const char* b3 = b2 + kstep;
;             PG8_LDB(B0, 0, 0); PG8_LDB(B1, 0, 1); PG8_SCHED; PG8_LDA(At, 0, 0); PG8_STAGE(PG8_SA(1, 1), a1 + hstepA, voffA);
;             PG8_WAIT_V(8); PG8_WAIT_L(0); PG8_BAR; PG8_MMA(0, 0, At, B0); PG8_MMA(0, 1, At, B1); PG8_BAR; PG8_SCHED;
;             PG8_LDA(At, 0, 1); PG8_STAGE(PG8_SB(0, 0), b2, voffB); PG8_STAGE(PG8_SB(0, 1), b2 + hstepB, voffB); PG8_STAGE(PG8_SA(0, 0), a2, voffA);
;             PG8_WAIT_V(8); PG8_WAIT_L(0); PG8_BAR; PG8_MMA(1, 0, At, B0); PG8_MMA(1, 1, At, B1); PG8_BAR; PG8_SCHED;
.LBB0_416:
	s_add_i32 s8, s2, 2
	s_add_u32 s9, s52, s0
	s_addc_u32 s3, s53, s1
	s_add_i32 s26, 0, 0x10000
	s_cmp_eq_u32 s65, s2
	s_cselect_b32 s3, s6, s3
	s_cselect_b32 s2, s7, s9
	v_add_u32_e32 v153, s26, v148
	s_cselect_b64 vcc, -1, 0
	s_add_i32 s9, 0, 0x14000
	v_lshl_add_u64 v[170:171], v[128:129], 0, s[0:1]
	ds_read_b128 v[154:157], v153
	ds_read_b128 v[158:161], v153 offset:1024
	ds_read_b128 v[162:165], v153 offset:2048
	ds_read_b128 v[166:169], v153 offset:3072
	v_add_u32_e32 v153, s9, v148
	v_cndmask_b32_e32 v205, v171, v151, vcc
	v_cndmask_b32_e32 v204, v170, v152, vcc
	ds_read_b128 v[170:173], v153
	ds_read_b128 v[174:177], v153 offset:1024
	ds_read_b128 v[178:181], v153 offset:2048
	ds_read_b128 v[188:191], v153 offset:3072
	v_lshl_add_u64 v[244:245], s[52:53], 0, v[146:147]
	s_add_i32 m0, s41, 0xc000
	ds_read_b128 v[192:195], v149
	ds_read_b128 v[196:199], v149 offset:1024
	ds_read_b128 v[200:203], v149 offset:2048
	ds_read_b128 v[224:227], v149 offset:3072
	ds_read_b128 v[228:231], v149 offset:4096
	ds_read_b128 v[232:235], v149 offset:5120
	ds_read_b128 v[236:239], v149 offset:6144
	ds_read_b128 v[240:243], v149 offset:7168
	global_load_lds_dwordx4 v[244:245], off
	v_lshl_add_u64 v[244:245], s[52:53], 0, v[144:145]
	s_add_i32 m0, s41, 0xe000
	s_nop 0
	global_load_lds_dwordx4 v[244:245], off
	s_waitcnt vmcnt(8)
	s_waitcnt lgkmcnt(0)
	s_barrier
	s_setprio 1
	s_waitcnt lgkmcnt(0)
	v_mfma_f32_16x16x32_bf16 v[124:127], v[154:157], v[192:195], v[124:127]
	v_mfma_f32_16x16x32_bf16 v[120:123], v[162:165], v[192:195], v[120:123]
	v_mfma_f32_16x16x32_bf16 v[116:119], v[154:157], v[200:203], v[116:119]
	v_mfma_f32_16x16x32_bf16 v[112:115], v[162:165], v[200:203], v[112:115]
	v_mfma_f32_16x16x32_bf16 v[108:111], v[154:157], v[228:231], v[108:111]
	v_mfma_f32_16x16x32_bf16 v[104:107], v[162:165], v[228:231], v[104:107]
	v_mfma_f32_16x16x32_bf16 v[100:103], v[154:157], v[236:239], v[100:103]
	v_mfma_f32_16x16x32_bf16 v[96:99], v[162:165], v[236:239], v[96:99]
	v_mfma_f32_16x16x32_bf16 v[124:127], v[158:161], v[196:199], v[124:127]
	v_mfma_f32_16x16x32_bf16 v[120:123], v[166:169], v[196:199], v[120:123]
	v_mfma_f32_16x16x32_bf16 v[116:119], v[158:161], v[224:227], v[116:119]
	v_mfma_f32_16x16x32_bf16 v[112:115], v[166:169], v[224:227], v[112:115]
	v_mfma_f32_16x16x32_bf16 v[108:111], v[158:161], v[232:235], v[108:111]
	v_mfma_f32_16x16x32_bf16 v[104:107], v[166:169], v[232:235], v[104:107]
	v_mfma_f32_16x16x32_bf16 v[100:103], v[158:161], v[240:243], v[100:103]
	v_mfma_f32_16x16x32_bf16 v[96:99], v[166:169], v[240:243], v[96:99]
	s_setprio 0
	s_setprio 1
	v_mfma_f32_16x16x32_bf16 v[92:95], v[170:173], v[192:195], v[92:95]
	v_mfma_f32_16x16x32_bf16 v[88:91], v[178:181], v[192:195], v[88:91]
	v_mfma_f32_16x16x32_bf16 v[84:87], v[170:173], v[200:203], v[84:87]
	v_mfma_f32_16x16x32_bf16 v[80:83], v[178:181], v[200:203], v[80:83]
	v_mfma_f32_16x16x32_bf16 v[76:79], v[170:173], v[228:231], v[76:79]
	v_mfma_f32_16x16x32_bf16 v[72:75], v[178:181], v[228:231], v[72:75]
	v_mfma_f32_16x16x32_bf16 v[68:71], v[170:173], v[236:239], v[68:71]
	v_mfma_f32_16x16x32_bf16 v[64:67], v[178:181], v[236:239], v[64:67]
	v_mfma_f32_16x16x32_bf16 v[92:95], v[174:177], v[196:199], v[92:95]
	v_mfma_f32_16x16x32_bf16 v[88:91], v[188:191], v[196:199], v[88:91]
	v_mfma_f32_16x16x32_bf16 v[84:87], v[174:177], v[224:227], v[84:87]
	v_mfma_f32_16x16x32_bf16 v[80:83], v[188:191], v[224:227], v[80:83]
	v_mfma_f32_16x16x32_bf16 v[76:79], v[174:177], v[232:235], v[76:79]
	v_mfma_f32_16x16x32_bf16 v[72:75], v[188:191], v[232:235], v[72:75]
	v_mfma_f32_16x16x32_bf16 v[68:71], v[174:177], v[240:243], v[68:71]
	v_mfma_f32_16x16x32_bf16 v[64:67], v[188:191], v[240:243], v[64:67]
	s_setprio 0
	s_barrier
	s_add_i32 s26, s26, s40
	v_lshl_add_u64 v[244:245], v[204:205], 0, v[132:133]
	s_mov_b32 m0, s26
	ds_read_b128 v[192:195], v149 offset:16384
	ds_read_b128 v[196:199], v149 offset:17408
	ds_read_b128 v[200:203], v149 offset:18432
	ds_read_b128 v[224:227], v149 offset:19456
	ds_read_b128 v[228:231], v149 offset:20480
	ds_read_b128 v[232:235], v149 offset:21504
	ds_read_b128 v[236:239], v149 offset:22528
	ds_read_b128 v[240:243], v149 offset:23552
	global_load_lds_dwordx4 v[244:245], off
	v_lshl_add_u64 v[246:247], v[204:205], 0, v[136:137]
	s_add_i32 m0, s26, 0x2000
	v_lshl_add_u64 v[204:205], v[204:205], 0, s[58:59]
	s_add_i32 s9, s9, s40
	global_load_lds_dwordx4 v[246:247], off
	v_lshl_add_u64 v[248:249], v[204:205], 0, v[132:133]
	s_mov_b32 m0, s9
	v_lshl_add_u64 v[204:205], v[204:205], 0, v[136:137]
	global_load_lds_dwordx4 v[248:249], off
	s_add_i32 m0, s9, 0x2000
	v_lshl_add_u64 v[250:251], s[2:3], 0, v[130:131]
	global_load_lds_dwordx4 v[204:205], off
	s_mov_b32 m0, s41
	v_lshl_add_u64 v[218:219], s[2:3], 0, v[134:135]
	global_load_lds_dwordx4 v[250:251], off
	s_mov_b32 m0, s49
	s_nop 0
	global_load_lds_dwordx4 v[218:219], off
	s_waitcnt vmcnt(8)
	s_waitcnt lgkmcnt(0)
	s_barrier
; #define PG8_STAGE(bufoff, gbase, voff) do { _Pragma("unroll") for (int _i = 0; _i < 2; ++_i) \
;         __builtin_amdgcn_global_load_lds((const unsigned*)((const char*)(gbase) + (voff)[_i]), (LAS unsigned*)(lds + (bufoff) + ldsw + _i * 8192), 16, 0, 0); } while (0)
; #define PG8_LDA(dst, b, h) do { _Pragma("unroll") for (int m = 0; m < 4; ++m) _Pragma("unroll") for (int k = 0; k < 2; ++k) dst[m][k] = *(const LAS bf16x8*)(lds + PG8_SA(b, h) + aoff + m * 2048 + k * 1024); } while (0)
; #define PG8_LDB(dst, b, h) do { _Pragma("unroll") for (int n = 0; n < 2; ++n) _Pragma("unroll") for (int k = 0; k < 2; ++k) dst[n][k] = *(const LAS bf16x8*)(lds + PG8_SB(b, h) + boff + n * 2048 + k * 1024); } while (0)
; #define PG8_MMA(ai, bj, At, Bt) do { __builtin_amdgcn_s_setprio(1); _Pragma("unroll") for (int m = 0; m < 4; ++m) _Pragma("unroll") for (int n = 0; n < 2; ++n) _Pragma("unroll") for (int k = 0; k < 2; ++k) \
;         acc[ai][bj][m][n] = __builtin_amdgcn_mfma_f32_16x16x32_bf16(Bt[n][k], At[m][k], acc[ai][bj][m][n], 0, 0, 0); __builtin_amdgcn_s_setprio(0); } while (0)
; #define PG8_WAIT_V(n) asm volatile("s_waitcnt vmcnt(" #n ")" ::: "memory")
; #define PG8_WAIT_L(n) asm volatile("s_waitcnt lgkmcnt(" #n ")" ::: "memory")
; #define PG8_BAR __builtin_amdgcn_s_barrier()
; #define PG8_SCHED __builtin_amdgcn_sched_barrier(0)
;     ...
;             PG8_WAIT_V(8); PG8_WAIT_L(0); PG8_BAR; PG8_MMA(1, 0, At, B0); PG8_MMA(1, 1, At, B1); PG8_BAR; PG8_SCHED;
;             PG8_LDB(B0, 1, 0); PG8_LDB(B1, 1, 1); PG8_SCHED; PG8_LDA(At, 1, 0); PG8_STAGE(PG8_SA(0, 1), a2 + hstepA, voffA);
;             PG8_WAIT_V(8); PG8_WAIT_L(0); PG8_BAR; PG8_MMA(0, 0, At, B0); PG8_MMA(0, 1, At, B1); PG8_BAR; PG8_SCHED;
	s_setprio 1
	s_waitcnt lgkmcnt(0)
	v_mfma_f32_16x16x32_bf16 v[60:63], v[154:157], v[192:195], v[60:63]
	v_mfma_f32_16x16x32_bf16 v[56:59], v[162:165], v[192:195], v[56:59]
	v_mfma_f32_16x16x32_bf16 v[52:55], v[154:157], v[200:203], v[52:55]
	v_mfma_f32_16x16x32_bf16 v[48:51], v[162:165], v[200:203], v[48:51]
	v_mfma_f32_16x16x32_bf16 v[44:47], v[154:157], v[228:231], v[44:47]
	v_mfma_f32_16x16x32_bf16 v[40:43], v[162:165], v[228:231], v[40:43]
	v_mfma_f32_16x16x32_bf16 v[36:39], v[154:157], v[236:239], v[36:39]
	v_mfma_f32_16x16x32_bf16 v[32:35], v[162:165], v[236:239], v[32:35]
	v_mfma_f32_16x16x32_bf16 v[60:63], v[158:161], v[196:199], v[60:63]
	v_mfma_f32_16x16x32_bf16 v[56:59], v[166:169], v[196:199], v[56:59]
	v_mfma_f32_16x16x32_bf16 v[52:55], v[158:161], v[224:227], v[52:55]
	v_mfma_f32_16x16x32_bf16 v[48:51], v[166:169], v[224:227], v[48:51]
	v_mfma_f32_16x16x32_bf16 v[44:47], v[158:161], v[232:235], v[44:47]
	v_mfma_f32_16x16x32_bf16 v[40:43], v[166:169], v[232:235], v[40:43]
	v_mfma_f32_16x16x32_bf16 v[36:39], v[158:161], v[240:243], v[36:39]
	v_mfma_f32_16x16x32_bf16 v[32:35], v[166:169], v[240:243], v[32:35]
	s_setprio 0
	s_setprio 1
	v_mfma_f32_16x16x32_bf16 v[28:31], v[170:173], v[192:195], v[28:31]
	v_mfma_f32_16x16x32_bf16 v[24:27], v[178:181], v[192:195], v[24:27]
	v_mfma_f32_16x16x32_bf16 v[20:23], v[170:173], v[200:203], v[20:23]
	v_mfma_f32_16x16x32_bf16 v[16:19], v[178:181], v[200:203], v[16:19]
	v_mfma_f32_16x16x32_bf16 v[12:15], v[170:173], v[228:231], v[12:15]
	v_mfma_f32_16x16x32_bf16 v[8:11], v[178:181], v[228:231], v[8:11]
	v_mfma_f32_16x16x32_bf16 v[4:7], v[170:173], v[236:239], v[4:7]
	v_mfma_f32_16x16x32_bf16 v[0:3], v[178:181], v[236:239], v[0:3]
	v_mfma_f32_16x16x32_bf16 v[28:31], v[174:177], v[196:199], v[28:31]
	v_mfma_f32_16x16x32_bf16 v[24:27], v[188:191], v[196:199], v[24:27]
	v_mfma_f32_16x16x32_bf16 v[20:23], v[174:177], v[224:227], v[20:23]
	v_mfma_f32_16x16x32_bf16 v[16:19], v[188:191], v[224:227], v[16:19]
	v_mfma_f32_16x16x32_bf16 v[12:15], v[174:177], v[232:235], v[12:15]
	v_mfma_f32_16x16x32_bf16 v[8:11], v[188:191], v[232:235], v[8:11]
	v_mfma_f32_16x16x32_bf16 v[4:7], v[174:177], v[240:243], v[4:7]
	v_mfma_f32_16x16x32_bf16 v[0:3], v[188:191], v[240:243], v[0:3]
	s_setprio 0
	s_barrier
	s_add_i32 s9, 0, 0x18000
	v_add_u32_e32 v153, s9, v148
	s_add_i32 s26, 0, 0x1c000
	ds_read_b128 v[154:157], v153
	ds_read_b128 v[158:161], v153 offset:1024
	ds_read_b128 v[162:165], v153 offset:2048
	ds_read_b128 v[166:169], v153 offset:3072
	v_add_u32_e32 v153, s26, v148
	ds_read_b128 v[170:173], v153
	ds_read_b128 v[174:177], v153 offset:1024
	ds_read_b128 v[178:181], v153 offset:2048
	ds_read_b128 v[188:191], v153 offset:3072
	s_add_u32 s2, s2, s58
	s_addc_u32 s3, s3, 0
	s_mov_b32 m0, s10
	v_lshl_add_u64 v[212:213], s[2:3], 0, v[130:131]
	ds_read_b128 v[192:195], v149 offset:32768
	ds_read_b128 v[196:199], v149 offset:33792
	ds_read_b128 v[200:203], v149 offset:34816
	ds_read_b128 v[224:227], v149 offset:35840
	ds_read_b128 v[228:231], v149 offset:36864
	ds_read_b128 v[232:235], v149 offset:37888
	ds_read_b128 v[236:239], v149 offset:38912
	ds_read_b128 v[240:243], v149 offset:39936
	global_load_lds_dwordx4 v[212:213], off
	v_lshl_add_u64 v[212:213], s[2:3], 0, v[134:135]
	s_mov_b32 m0, s11
	s_nop 0
	global_load_lds_dwordx4 v[212:213], off
	s_waitcnt vmcnt(8)
	s_waitcnt lgkmcnt(0)
	s_barrier
	s_setprio 1
	s_waitcnt lgkmcnt(0)
	v_mfma_f32_16x16x32_bf16 v[124:127], v[154:157], v[192:195], v[124:127]
	v_mfma_f32_16x16x32_bf16 v[120:123], v[162:165], v[192:195], v[120:123]
	v_mfma_f32_16x16x32_bf16 v[116:119], v[154:157], v[200:203], v[116:119]
	v_mfma_f32_16x16x32_bf16 v[112:115], v[162:165], v[200:203], v[112:115]
	v_mfma_f32_16x16x32_bf16 v[108:111], v[154:157], v[228:231], v[108:111]
	v_mfma_f32_16x16x32_bf16 v[104:107], v[162:165], v[228:231], v[104:107]
	v_mfma_f32_16x16x32_bf16 v[100:103], v[154:157], v[236:239], v[100:103]
	v_mfma_f32_16x16x32_bf16 v[96:99], v[162:165], v[236:239], v[96:99]
	v_mfma_f32_16x16x32_bf16 v[124:127], v[158:161], v[196:199], v[124:127]
	v_mfma_f32_16x16x32_bf16 v[120:123], v[166:169], v[196:199], v[120:123]
	v_mfma_f32_16x16x32_bf16 v[116:119], v[158:161], v[224:227], v[116:119]
	v_mfma_f32_16x16x32_bf16 v[112:115], v[166:169], v[224:227], v[112:115]
	v_mfma_f32_16x16x32_bf16 v[108:111], v[158:161], v[232:235], v[108:111]
	v_mfma_f32_16x16x32_bf16 v[104:107], v[166:169], v[232:235], v[104:107]
	v_mfma_f32_16x16x32_bf16 v[100:103], v[158:161], v[240:243], v[100:103]
	v_mfma_f32_16x16x32_bf16 v[96:99], v[166:169], v[240:243], v[96:99]
	s_setprio 0
	s_setprio 1
	v_mfma_f32_16x16x32_bf16 v[92:95], v[170:173], v[192:195], v[92:95]
	v_mfma_f32_16x16x32_bf16 v[88:91], v[178:181], v[192:195], v[88:91]
	v_mfma_f32_16x16x32_bf16 v[84:87], v[170:173], v[200:203], v[84:87]
	v_mfma_f32_16x16x32_bf16 v[80:83], v[178:181], v[200:203], v[80:83]
	v_mfma_f32_16x16x32_bf16 v[76:79], v[170:173], v[228:231], v[76:79]
	v_mfma_f32_16x16x32_bf16 v[72:75], v[178:181], v[228:231], v[72:75]
	v_mfma_f32_16x16x32_bf16 v[68:71], v[170:173], v[236:239], v[68:71]
	v_mfma_f32_16x16x32_bf16 v[64:67], v[178:181], v[236:239], v[64:67]
	v_mfma_f32_16x16x32_bf16 v[92:95], v[174:177], v[196:199], v[92:95]
	v_mfma_f32_16x16x32_bf16 v[88:91], v[188:191], v[196:199], v[88:91]
	v_mfma_f32_16x16x32_bf16 v[84:87], v[174:177], v[224:227], v[84:87]
	v_mfma_f32_16x16x32_bf16 v[80:83], v[188:191], v[224:227], v[80:83]
	v_mfma_f32_16x16x32_bf16 v[76:79], v[174:177], v[232:235], v[76:79]
	v_mfma_f32_16x16x32_bf16 v[72:75], v[188:191], v[232:235], v[72:75]
	v_mfma_f32_16x16x32_bf16 v[68:71], v[174:177], v[240:243], v[68:71]
	v_mfma_f32_16x16x32_bf16 v[64:67], v[188:191], v[240:243], v[64:67]
	s_setprio 0
	s_barrier
; #define PG8_STAGE(bufoff, gbase, voff) do { _Pragma("unroll") for (int _i = 0; _i < 2; ++_i) \
;         __builtin_amdgcn_global_load_lds((const unsigned*)((const char*)(gbase) + (voff)[_i]), (LAS unsigned*)(lds + (bufoff) + ldsw + _i * 8192), 16, 0, 0); } while (0)
; #define PG8_LDA(dst, b, h) do { _Pragma("unroll") for (int m = 0; m < 4; ++m) _Pragma("unroll") for (int k = 0; k < 2; ++k) dst[m][k] = *(const LAS bf16x8*)(lds + PG8_SA(b, h) + aoff + m * 2048 + k * 1024); } while (0)
; #define PG8_MMA(ai, bj, At, Bt) do { __builtin_amdgcn_s_setprio(1); _Pragma("unroll") for (int m = 0; m < 4; ++m) _Pragma("unroll") for (int n = 0; n < 2; ++n) _Pragma("unroll") for (int k = 0; k < 2; ++k) \
;         acc[ai][bj][m][n] = __builtin_amdgcn_mfma_f32_16x16x32_bf16(Bt[n][k], At[m][k], acc[ai][bj][m][n], 0, 0, 0); __builtin_amdgcn_s_setprio(0); } while (0)
; #define PG8_WAIT_V(n) asm volatile("s_waitcnt vmcnt(" #n ")" ::: "memory")
; #define PG8_WAIT_L(n) asm volatile("s_waitcnt lgkmcnt(" #n ")" ::: "memory")
; #define PG8_BAR __builtin_amdgcn_s_barrier()
; #define PG8_SCHED __builtin_amdgcn_sched_barrier(0)
;     ...
;             PG8_LDA(At, 1, 1); PG8_STAGE(PG8_SB(1, 0), b3, voffB); PG8_STAGE(PG8_SB(1, 1), b3 + hstepB, voffB); PG8_STAGE(PG8_SA(1, 0), a3, voffA);
;             PG8_WAIT_V(8); PG8_WAIT_L(0); PG8_BAR; PG8_MMA(1, 0, At, B0); PG8_MMA(1, 1, At, B1); PG8_BAR; PG8_SCHED;
;         }
;         if (wr == 0) PG8_BAR;
	s_add_i32 s2, s9, s40
	s_add_i32 m0, s2, 0xffffff80
	ds_read_b128 v[192:195], v149 offset:49152
	ds_read_b128 v[196:199], v149 offset:50176
	ds_read_b128 v[200:203], v149 offset:51200
	ds_read_b128 v[224:227], v149 offset:52224
	ds_read_b128 v[228:231], v149 offset:53248
	ds_read_b128 v[232:235], v149 offset:54272
	ds_read_b128 v[236:239], v149 offset:55296
	ds_read_b128 v[240:243], v149 offset:56320
	global_load_lds_dwordx4 v[244:245], off offset:128
	s_add_i32 m0, s2, 0x1f80
	s_add_i32 s2, s26, s40
	global_load_lds_dwordx4 v[246:247], off offset:128
	s_add_i32 m0, s2, 0xffffff80
	s_nop 0
	global_load_lds_dwordx4 v[248:249], off offset:128
	s_add_i32 m0, s2, 0x1f80
	s_nop 0
	global_load_lds_dwordx4 v[204:205], off offset:128
	s_add_i32 m0, s51, 0xffffff80
	s_nop 0
	global_load_lds_dwordx4 v[250:251], off offset:128
	s_add_i32 m0, s64, 0xffffff80
	s_nop 0
	global_load_lds_dwordx4 v[218:219], off offset:128
	s_waitcnt vmcnt(8)
	s_waitcnt lgkmcnt(0)
	s_barrier
	s_setprio 1
	s_waitcnt lgkmcnt(0)
	v_mfma_f32_16x16x32_bf16 v[60:63], v[154:157], v[192:195], v[60:63]
	v_mfma_f32_16x16x32_bf16 v[56:59], v[162:165], v[192:195], v[56:59]
	v_mfma_f32_16x16x32_bf16 v[52:55], v[154:157], v[200:203], v[52:55]
	v_mfma_f32_16x16x32_bf16 v[48:51], v[162:165], v[200:203], v[48:51]
	v_mfma_f32_16x16x32_bf16 v[44:47], v[154:157], v[228:231], v[44:47]
	v_mfma_f32_16x16x32_bf16 v[40:43], v[162:165], v[228:231], v[40:43]
	v_mfma_f32_16x16x32_bf16 v[36:39], v[154:157], v[236:239], v[36:39]
	v_mfma_f32_16x16x32_bf16 v[32:35], v[162:165], v[236:239], v[32:35]
	v_mfma_f32_16x16x32_bf16 v[60:63], v[158:161], v[196:199], v[60:63]
	v_mfma_f32_16x16x32_bf16 v[56:59], v[166:169], v[196:199], v[56:59]
	v_mfma_f32_16x16x32_bf16 v[52:55], v[158:161], v[224:227], v[52:55]
	v_mfma_f32_16x16x32_bf16 v[48:51], v[166:169], v[224:227], v[48:51]
	v_mfma_f32_16x16x32_bf16 v[44:47], v[158:161], v[232:235], v[44:47]
	v_mfma_f32_16x16x32_bf16 v[40:43], v[166:169], v[232:235], v[40:43]
	v_mfma_f32_16x16x32_bf16 v[36:39], v[158:161], v[240:243], v[36:39]
	v_mfma_f32_16x16x32_bf16 v[32:35], v[166:169], v[240:243], v[32:35]
	s_setprio 0
	s_setprio 1
	v_mfma_f32_16x16x32_bf16 v[28:31], v[170:173], v[192:195], v[28:31]
	v_mfma_f32_16x16x32_bf16 v[24:27], v[178:181], v[192:195], v[24:27]
	v_mfma_f32_16x16x32_bf16 v[20:23], v[170:173], v[200:203], v[20:23]
	v_mfma_f32_16x16x32_bf16 v[16:19], v[178:181], v[200:203], v[16:19]
	v_mfma_f32_16x16x32_bf16 v[12:15], v[170:173], v[228:231], v[12:15]
	v_mfma_f32_16x16x32_bf16 v[8:11], v[178:181], v[228:231], v[8:11]
	v_mfma_f32_16x16x32_bf16 v[4:7], v[170:173], v[236:239], v[4:7]
	v_mfma_f32_16x16x32_bf16 v[0:3], v[178:181], v[236:239], v[0:3]
	v_mfma_f32_16x16x32_bf16 v[28:31], v[174:177], v[196:199], v[28:31]
	v_mfma_f32_16x16x32_bf16 v[24:27], v[188:191], v[196:199], v[24:27]
	v_mfma_f32_16x16x32_bf16 v[20:23], v[174:177], v[224:227], v[20:23]
	v_mfma_f32_16x16x32_bf16 v[16:19], v[188:191], v[224:227], v[16:19]
	v_mfma_f32_16x16x32_bf16 v[12:15], v[174:177], v[232:235], v[12:15]
	v_mfma_f32_16x16x32_bf16 v[8:11], v[188:191], v[232:235], v[8:11]
	v_mfma_f32_16x16x32_bf16 v[4:7], v[174:177], v[240:243], v[4:7]
	v_mfma_f32_16x16x32_bf16 v[0:3], v[188:191], v[240:243], v[0:3]
	s_setprio 0
	s_barrier
	s_add_u32 s0, s0, 0x100
	s_addc_u32 s1, s1, 0
	v_lshl_add_u64 v[146:147], v[146:147], 0, s[94:95]
	v_lshl_add_u64 v[144:145], v[144:145], 0, s[94:95]
	s_cmp_ge_u32 s8, s48
	s_mov_b32 s2, s8
	s_cbranch_scc0 .LBB0_416
	v_readlane_b32 s0, v254, 45
	v_readlane_b32 s1, v254, 46
	s_and_b64 vcc, exec, s[0:1]
	s_cbranch_vccz .LBB0_419
	s_barrier
